# FFN norm f16 rows: row data prefetched one iteration ahead AND the adaLN wait moved from the join to just before first use (after reduce+divide), on keep_v8
# speedup vs baseline: 1.0114x; 1.0041x over previous
.Lnf_join:
	v_mul_f32_e32 v40, v18, v18
	v_mul_f32_e32 v44, v19, v19
	v_mul_f32_e32 v42, v20, v20
	v_mul_f32_e32 v38, v21, v21
	v_pk_add_f32 v[40:41], v[40:41], v[44:45]
	v_pk_add_f32 v[38:39], v[42:43], v[38:39]
	s_min_i32 s2, s24, 0x8000
	v_pk_add_f32 v[38:39], v[40:41], v[38:39]
	s_ashr_i32 s2, s2, 11
	v_add_f32_e32 v0, v38, v39
	ds_bpermute_b32 v38, v35, v0
	s_mul_hi_i32 s3, s2, 0x9000
	s_mul_i32 s2, s2, 0x9000
	s_add_u32 s4, s28, s2
	s_addc_u32 s5, s29, s3
	s_waitcnt lgkmcnt(0)
	v_add_f32_e32 v0, v0, v38
	ds_bpermute_b32 v38, v48, v0
	s_add_u32 s96, s4, 0x1000
	s_addc_u32 s97, s5, 0
	v_lshlrev_b32_e32 v46, 2, v34
	s_add_i32 s24, s24, s10
	s_waitcnt lgkmcnt(0)
	v_add_f32_e32 v0, v0, v38
	ds_bpermute_b32 v38, v49, v0
	s_cmp_lt_i32 s24, s20
	s_waitcnt lgkmcnt(0)
	v_add_f32_e32 v0, v0, v38
	ds_bpermute_b32 v38, v50, v0
	s_waitcnt lgkmcnt(0)
	v_add_f32_e32 v0, v0, v38
	ds_bpermute_b32 v38, v51, v0
	s_waitcnt lgkmcnt(0)
	v_add_f32_e32 v0, v0, v38
	ds_bpermute_b32 v38, v52, v0
	s_waitcnt lgkmcnt(0)
	v_add_f32_e32 v0, v0, v38
	v_fmamk_f32 v0, v0, 0x3a800000, v240
	v_cmp_gt_f32_e32 vcc, s77, v0
	v_mul_f32_e32 v38, 0x4f800000, v0
	s_nop 0
	v_cndmask_b32_e32 v0, v0, v38, vcc
	v_sqrt_f32_e32 v38, v0
	s_nop 0
	v_add_u32_e32 v39, -1, v38
	v_fma_f32 v40, -v39, v38, v0
	v_cmp_ge_f32_e64 s[2:3], 0, v40
	v_add_u32_e32 v40, 1, v38
	s_nop 0
	v_cndmask_b32_e64 v39, v38, v39, s[2:3]
	v_fma_f32 v38, -v40, v38, v0
	v_cmp_lt_f32_e64 s[2:3], 0, v38
	s_nop 1
	v_cndmask_b32_e64 v38, v39, v40, s[2:3]
	v_mul_f32_e32 v39, 0x37800000, v38
	v_cndmask_b32_e32 v38, v38, v39, vcc
	v_cmp_class_f32_e32 vcc, v0, v241
	s_nop 1
	v_cndmask_b32_e32 v0, v38, v0, vcc
	v_div_scale_f32 v38, s[2:3], v0, v0, 1.0
	v_rcp_f32_e32 v39, v38
	s_nop 0
	v_fma_f32 v40, -v38, v39, 1.0
	v_fmac_f32_e32 v39, v40, v39
	v_div_scale_f32 v40, vcc, 1.0, v0, 1.0
	v_mul_f32_e32 v41, v40, v39
	v_fma_f32 v42, -v38, v41, v40
	v_fmac_f32_e32 v41, v42, v39
	v_fma_f32 v38, -v38, v41, v40
	v_div_fmas_f32 v38, v38, v39, v41
	v_div_fixup_f32 v0, v38, v0, 1.0
	v_pk_mul_f32 v[32:33], v[32:33], v[0:1] op_sel_hi:[1,0]
	v_pk_mul_f32 v[30:31], v[30:31], v[0:1] op_sel_hi:[1,0]
	v_pk_mul_f32 v[32:33], v[4:5], v[32:33]
	v_pk_mul_f32 v[30:31], v[2:3], v[30:31]
	v_pk_mul_f32 v[28:29], v[28:29], v[0:1] op_sel_hi:[1,0]
	v_pk_mul_f32 v[26:27], v[26:27], v[0:1] op_sel_hi:[1,0]
	v_pk_mul_f32 v[28:29], v[8:9], v[28:29]
	v_pk_mul_f32 v[26:27], v[6:7], v[26:27]
	v_pk_mul_f32 v[24:25], v[24:25], v[0:1] op_sel_hi:[1,0]
	v_pk_mul_f32 v[22:23], v[22:23], v[0:1] op_sel_hi:[1,0]
	v_pk_mul_f32 v[24:25], v[12:13], v[24:25]
	v_pk_mul_f32 v[22:23], v[10:11], v[22:23]
	v_pk_mul_f32 v[20:21], v[20:21], v[0:1] op_sel_hi:[1,0]
	v_pk_mul_f32 v[18:19], v[18:19], v[0:1] op_sel_hi:[1,0]
	v_pk_mul_f32 v[20:21], v[16:17], v[20:21]
	v_pk_mul_f32 v[18:19], v[14:15], v[18:19]
	s_waitcnt vmcnt(4)
	v_pk_add_f32 v[118:119], v[118:119], 1.0 op_sel_hi:[1,0]
	v_pk_add_f32 v[116:117], v[116:117], 1.0 op_sel_hi:[1,0]
	v_pk_add_f32 v[122:123], v[122:123], 1.0 op_sel_hi:[1,0]
	v_pk_add_f32 v[120:121], v[120:121], 1.0 op_sel_hi:[1,0]
	v_pk_fma_f32 v[32:33], v[118:119], v[32:33], v[102:103]
	v_pk_fma_f32 v[30:31], v[116:117], v[30:31], v[100:101]
	v_pk_add_f32 v[126:127], v[126:127], 1.0 op_sel_hi:[1,0]
	v_pk_add_f32 v[124:125], v[124:125], 1.0 op_sel_hi:[1,0]
	v_cvt_pk_bf16_f32 v30, v30, v31
	v_cvt_pk_bf16_f32 v31, v32, v33
	global_store_dwordx2 v[36:37], v[30:31], off
	v_pk_fma_f32 v[28:29], v[122:123], v[28:29], v[106:107]
	v_pk_fma_f32 v[26:27], v[120:121], v[26:27], v[104:105]
	v_pk_add_f32 v[130:131], v[130:131], 1.0 op_sel_hi:[1,0]
	v_pk_add_f32 v[128:129], v[128:129], 1.0 op_sel_hi:[1,0]
	v_cvt_pk_bf16_f32 v26, v26, v27
	v_cvt_pk_bf16_f32 v27, v28, v29
	global_store_dwordx2 v[36:37], v[26:27], off offset:512
	v_pk_fma_f32 v[24:25], v[126:127], v[24:25], v[110:111]
	v_pk_fma_f32 v[22:23], v[124:125], v[22:23], v[108:109]
	s_nop 0
	v_cvt_pk_bf16_f32 v22, v22, v23
	v_cvt_pk_bf16_f32 v23, v24, v25
	global_store_dwordx2 v[36:37], v[22:23], off offset:1024
	v_pk_fma_f32 v[20:21], v[130:131], v[20:21], v[114:115]
	v_pk_fma_f32 v[18:19], v[128:129], v[18:19], v[112:113]
	s_nop 0
	v_cvt_pk_bf16_f32 v18, v18, v19
	v_cvt_pk_bf16_f32 v19, v20, v21
	global_store_dwordx2 v[36:37], v[18:19], off offset:1536
	v_lshl_add_u64 v[36:37], v[36:37], 0, s[56:57]
	s_cbranch_scc0 .LBB0_784
